# WG stagger: workgroups with blockIdx bit 3 set sleep ~7us at entry of the four big GEMM phases so epilogue HBM bursts of the two halves do not coincide
# speedup vs baseline: 1.0102x; 1.0085x over previous
;   DI bf16_t* wt_in0() const { return (bf16_t*)(ws + OFF_WT_IN0); }
;   DI bf16_t* h() const { return (bf16_t*)(ws + OFF_H); }
; DI void phase_gemm_in0(const Params& p, char* smem) {
;   u32x4 ra[4], rb[4]; bool pre = false;
;   for (int t = blockIdx.x; t < 64 * 16; t += gridDim.x) {
;     const int mt = t & 63, nt = t >> 6, tn = t + gridDim.x;
;     const bool has_next = tn < 64 * 16;
;     const GTile tl{p.h(), D, p.wt_in0(), D, D, mt * 256, nt * 256}, nx{p.h(), D, p.wt_in0(), D, D, (tn & 63) * 256, (tn >> 6) * 256};
;     WAVE_GEOM;
;     const bool trans = nt == 12 && wn_ >= 2;
.Lgs_185:
	s_or_b64 exec, exec, s[0:1]
	s_bitcmp1_b32 s84, 3
	s_cbranch_scc0 .Lstag_1
	s_sleep 127
	s_sleep 127
.Lstag_1:
	s_cmpk_lt_i32 s84, 0x400
	s_cselect_b64 s[0:1], -1, 0
	v_writelane_b32 v252, s0, 39
	s_cmpk_gt_i32 s84, 0x3ff
	s_waitcnt lgkmcnt(0)
	s_barrier
	v_writelane_b32 v252, s1, 40
	s_cbranch_scc1 .LBB0_129
	s_add_u32 s16, s22, 0x40c0000
	s_addc_u32 s17, s23, 0
	s_add_u32 s6, s22, 0xc00000
	s_addc_u32 s7, s23, 0
	s_add_u32 s8, s22, 0xc00080
	s_addc_u32 s9, s23, 0
	s_add_u32 s10, s22, 0xc40080
	s_addc_u32 s11, s23, 0
	s_add_u32 s12, s22, 0xc80080
	s_addc_u32 s13, s23, 0
	s_add_u32 s14, s22, 0xcc0080
	s_addc_u32 s15, s23, 0
	s_add_u32 s26, s22, 0xc40000
	s_addc_u32 s27, s23, 0
	s_add_u32 s28, s22, 0xc80000
	s_addc_u32 s29, s23, 0
	s_add_u32 s30, s22, 0x150c0000
	s_addc_u32 s31, s23, 0
	s_add_u32 s18, s22, 0x80c0000
	s_addc_u32 s19, s23, 0
	s_add_i32 s0, s84, s96
	s_lshl_b32 s24, s84, 8
	s_lshl_b32 s25, s96, 8
	s_lshl_b32 s36, s0, 19
	s_lshl_b32 s37, s96, 19
	s_lshl_b32 s38, s0, 2
	s_lshl_b32 s39, s96, 2
	s_mov_b64 s[0:1], 0
	v_mov_b32_e32 v193, 0
	s_mov_b32 s40, 0x40000
	s_mov_b32 s41, 0x80000
	s_mov_b32 s44, 0xc0000
	s_movk_i32 s45, 0x90
	s_mov_b64 s[34:35], 0x40000
	s_mov_b64 s[42:43], 0x80000
	s_movk_i32 s46, 0x2200
	s_mov_b32 s47, s84
	s_branch .LBB0_98

;   DI bf16_t* h() const { return (bf16_t*)(ws + OFF_H); }
; DI void phase_gemm_out(const Params& p, char* smem, const bf16_t* Wt, const float* R, float* O) {
;   u32x4 ra[4], rb[4]; bool pre = false;
;   for (int t = blockIdx.x; t < 64 * 8; t += gridDim.x) {
;     const int mt = t & 63, nt = t >> 6, tn = t + gridDim.x;
;     const bool has_next = tn < 64 * 8;
;     const GTile tl{p.h(), D, Wt, D, D, mt * 256, nt * 256}, nx{p.h(), D, Wt, D, D, (tn & 63) * 256, (tn >> 6) * 256};
;     WAVE_GEOM;
.Lstag_6:
	v_cndmask_b32_e64 v0, 0, 1, s[6:7]
	v_cmp_ne_u32_e64 s[74:75], 1, v0
	s_andn2_b64 vcc, exec, s[6:7]
	s_waitcnt lgkmcnt(0)
	s_barrier
	s_cbranch_vccnz .LBB0_767
	s_add_u32 s16, s22, 0x1100000
	s_addc_u32 s17, s23, 0
	s_add_u32 s18, s22, 0x40c0000
	s_addc_u32 s19, s23, 0
	s_add_i32 s0, s84, s96
	s_lshl_b32 s24, s84, 2
	s_lshl_b32 s25, s96, 2
	s_lshl_b32 s26, s84, 8
	s_lshl_b32 s27, s96, 8
	s_lshl_b32 s28, s0, 19
	s_lshl_b32 s29, s96, 19
	s_mov_b64 s[12:13], 0
	v_mov_b32_e32 v185, 0
	s_mov_b32 s30, 0x40000
	s_mov_b32 s31, 0x80000
	s_mov_b32 s34, 0xc0000
	s_movk_i32 s35, 0x90
	s_mov_b64 s[0:1], 0x40000
	s_mov_b64 s[8:9], 0x80000
	s_add_i32 s36, 16, 0x12000
	s_add_i32 s37, 16, 0x1b000
	s_mov_b32 s38, s84
	s_branch .LBB0_745

;   DI bf16_t* wt_in1() const { return (bf16_t*)(ws + OFF_WT_IN1); }
;   DI bf16_t* h() const { return (bf16_t*)(ws + OFF_H); }
; DI int in1_nt(int t) { return (t >> 6) < 23 ? (t >> 6) : 25; }
; DI void phase_gemm_in1(const Params& p, char* smem) {
;   u32x4 ra[4], rb[4]; bool pre = false;
;   for (int t = blockIdx.x; t < 64 * 24; t += gridDim.x) {
;     const int mt = t & 63, nt = in1_nt(t), tn = t + gridDim.x;
;     const bool has_next = tn < 64 * 24;
;     const GTile tl{p.h(), D, p.wt_in1(), D, D, mt * 256, nt * 256}, nx{p.h(), D, p.wt_in1(), D, D, (tn & 63) * 256, in1_nt(tn) * 256};
;     WAVE_GEOM;
.Lstag_8:
	s_cmpk_gt_i32 s84, 0x5ff
	s_waitcnt lgkmcnt(0)
	s_barrier
	s_cbranch_scc1 .LBB0_913
	s_add_u32 s24, s22, 0x40c0000
	s_addc_u32 s25, s23, 0
	s_add_u32 s27, s22, 0x1980000
	s_addc_u32 s40, s23, 0
	s_add_u32 s0, s22, 0x1c6c0000
	s_addc_u32 s1, s23, 0
	s_add_u32 s41, s22, 0x80c0000
	s_addc_u32 s46, s23, 0
	s_add_u32 s8, s22, 0x3fc0000
	s_addc_u32 s9, s23, 0
	s_add_u32 s10, s22, 0x1a4c0000
	s_addc_u32 s11, s23, 0
	s_add_i32 s2, s84, s96
	s_lshl_b32 s47, s84, 8
	s_lshl_b32 s48, s96, 8
	s_lshl_b32 s49, s2, 19
	s_lshl_b32 s50, s96, 19
	s_mov_b64 s[6:7], 0
	v_mov_b32_e32 v193, 0
	s_mov_b32 s51, 0x40000
	s_mov_b32 s52, 0x80000
	s_mov_b32 s53, 0xc0000
	s_movk_i32 s54, 0x90
	s_mov_b64 s[12:13], 0x40000
	s_mov_b64 s[14:15], 0x80000
	s_movk_i32 s55, 0x3300
	s_mov_b64 s[28:29], 0x1a4c0040
	s_mov_b32 s56, s84
	s_branch .LBB0_877

;   DI bf16_t* h() const { return (bf16_t*)(ws + OFF_H); }
; DI void phase_gemm_out(const Params& p, char* smem, const bf16_t* Wt, const float* R, float* O) {
;   u32x4 ra[4], rb[4]; bool pre = false;
;   for (int t = blockIdx.x; t < 64 * 8; t += gridDim.x) {
;     const int mt = t & 63, nt = t >> 6, tn = t + gridDim.x;
;     const bool has_next = tn < 64 * 8;
;     const GTile tl{p.h(), D, Wt, D, D, mt * 256, nt * 256}, nx{p.h(), D, Wt, D, D, (tn & 63) * 256, (tn >> 6) * 256};
;     WAVE_GEOM;
.Lstag_11:
	s_and_b64 vcc, exec, s[74:75]
	s_waitcnt lgkmcnt(0)
	s_barrier
	s_cbranch_vccnz .LBB0_1655
	s_add_u32 s14, s22, 0x37c0000
	s_addc_u32 s15, s23, 0
	s_add_i32 s0, s84, s96
	s_lshl_b32 s16, s84, 2
	s_lshl_b32 s17, s96, 2
	s_lshl_b32 s18, s84, 8
	s_lshl_b32 s19, s96, 8
	s_lshl_b32 s24, s0, 19
	s_lshl_b32 s25, s96, 19
	s_mov_b64 s[10:11], 0
	v_mov_b32_e32 v185, 0
	s_mov_b32 s27, 0x40000
	s_mov_b32 s30, 0x80000
	s_mov_b32 s31, 0xc0000
	s_movk_i32 s33, 0x90
	s_mov_b64 s[0:1], 0x40000
	s_mov_b64 s[6:7], 0x80000
	s_add_i32 s34, 16, 0x12000
	s_add_i32 s35, 16, 0x1b000
	s_branch .LBB0_1633
